# P0 row-norm loop and P5 output loop: prefetch waits moved from the loop top to the register rotation (counted vmcnt); plus A3, A1, A6 rewrites
# baseline (speedup 1.0000x reference)
; __device__ __forceinline__ void p0_prologue(const Args& A, LAS unsigned char* lds, int tid, int lane, int wave) {
;     ...
;     f32x4 gv[4];
; #pragma unroll
;     for (int j = 0; j < 4; ++j) gv[j] = *((const f32x4*)A.g_norm + lane + 64 * j);
;     {
;         f32x4 v[4], nv[4]; f32x4 pv, npv;
;         int m = gw;
;         if (m < MTOT) { const float* xrow = m < MP ? A.x_prompt + (size_t)m * DM : A.x_sample + (size_t)(m - MP) * DM; const float* prow = m < MP ? A.p_prompt + (size_t)m * PLE : A.p_sample + (size_t)(m - MP) * PLE;
; #pragma unroll
;             for (int j = 0; j < 4; ++j) v[j] = *((const f32x4*)xrow + lane + 64 * j);
;             pv = *((const f32x4*)prow + lane); }
;         for (; m < MTOT; m += NGW) {
;             const int mn = m + NGW;
;             if (mn < MTOT) { const float* xrow = mn < MP ? A.x_prompt + (size_t)mn * DM : A.x_sample + (size_t)(mn - MP) * DM; const float* prow = mn < MP ? A.p_prompt + (size_t)mn * PLE : A.p_sample + (size_t)(mn - MP) * PLE;
; #pragma unroll
;                 for (int j = 0; j < 4; ++j) nv[j] = *((const f32x4*)xrow + lane + 64 * j);
;                 npv = *((const f32x4*)prow + lane); }
;             float s = 0.f;
; #pragma unroll
;             for (int j = 0; j < 4; ++j) s += (v[j].x * v[j].x + v[j].y * v[j].y) + (v[j].z * v[j].z + v[j].w * v[j].w);
;             const float rstd = __builtin_amdgcn_rsqf(wave_sum(s) * (1.f / DM) + NORM_EPS);
.LBB0_90:
	s_or_b64 exec, exec, s[0:1]
	v_readlane_b32 s0, v249, 8
	v_readlane_b32 s1, v249, 9
	s_cmp_lt_i32 s0, 0x8400
	s_cselect_b64 s[0:1], -1, 0
	v_mov_b32_e32 v131, 0
	v_writelane_b32 v249, s0, 30
	s_and_b64 vcc, exec, s[0:1]
	v_lshlrev_b32_e32 v128, 4, v145
	v_mbcnt_lo_u32_b32 v162, -1, 0
	v_lshlrev_b32_e32 v130, 3, v145
	v_writelane_b32 v249, s1, 31
	s_cbranch_vccz .LBB0_95
	global_load_dwordx4 v[2:5], v128, s[18:19] offset:3072
	global_load_dwordx4 v[6:9], v128, s[18:19] offset:2048
	global_load_dwordx4 v[10:13], v128, s[18:19] offset:1024
	global_load_dwordx4 v[14:17], v128, s[18:19]
	v_readlane_b32 s18, v249, 8
	v_readlane_b32 s19, v249, 9
	s_add_i32 s0, s18, 0xffff8000
	s_ashr_i32 s19, s18, 31
	s_cmp_lt_i32 s18, 0x8000
	v_readlane_b32 s36, v249, 14
	s_cselect_b32 s1, s19, 0
	s_cselect_b32 s0, s18, s0
	v_readlane_b32 s37, v249, 15
	v_readlane_b32 s38, v249, 16
	v_readlane_b32 s39, v249, 17
	v_readlane_b32 s48, v249, 26
	v_readlane_b32 s49, v249, 27
	v_readlane_b32 s50, v249, 28
	v_readlane_b32 s51, v249, 29
	s_cselect_b32 s3, s37, s39
	s_cselect_b32 s6, s36, s38
	s_cselect_b32 s7, s49, s51
	s_cselect_b32 s8, s48, s50
	s_lshl_b64 s[4:5], s[0:1], 12
	s_add_u32 s4, s6, s4
	s_addc_u32 s5, s3, s5
	s_lshl_b64 s[0:1], s[0:1], 10
	s_add_u32 s0, s8, s0
	s_addc_u32 s1, s7, s1
	global_load_dwordx4 v[34:37], v128, s[4:5]
	global_load_dwordx4 v[30:33], v128, s[4:5] offset:1024
	global_load_dwordx4 v[26:29], v128, s[4:5] offset:2048
	global_load_dwordx4 v[22:25], v128, s[4:5] offset:3072
	global_load_dwordx4 v[18:21], v128, s[0:1]
	v_mbcnt_hi_u32_b32 v38, -1, v162
	v_and_b32_e32 v1, 64, v38
	v_add_u32_e32 v39, 64, v1
	v_xor_b32_e32 v1, 1, v38
	v_cmp_lt_i32_e32 vcc, v1, v39
	v_xor_b32_e32 v40, 2, v38
	s_lshl_b64 s[0:1], s[18:19], 9
	v_cndmask_b32_e32 v1, v38, v1, vcc
	v_cmp_lt_i32_e32 vcc, v40, v39
	s_add_u32 s0, s96, s0
	s_addc_u32 s1, s97, s1
	v_cndmask_b32_e32 v40, v38, v40, vcc
	v_lshlrev_b32_e32 v58, 2, v40
	v_xor_b32_e32 v40, 4, v38
	v_cmp_lt_i32_e32 vcc, v40, v39
	s_add_u32 s0, s0, 0x5000000
	v_readlane_b32 s4, v249, 6
	v_cndmask_b32_e32 v40, v38, v40, vcc
	v_lshlrev_b32_e32 v59, 2, v40
	v_xor_b32_e32 v40, 8, v38
	v_cmp_lt_i32_e32 vcc, v40, v39
	s_addc_u32 s1, s1, 0
	v_readlane_b32 s5, v249, 7
	v_cndmask_b32_e32 v40, v38, v40, vcc
	v_lshlrev_b32_e32 v60, 2, v40
	v_xor_b32_e32 v40, 16, v38
	v_cmp_lt_i32_e32 vcc, v40, v39
	s_mov_b32 s10, s4
	s_ashr_i32 s11, s4, 31
	v_cndmask_b32_e32 v40, v38, v40, vcc
	s_lshl_b64 s[4:5], s[10:11], 9
	s_lshl_b64 s[6:7], s[18:19], 11
	v_lshlrev_b32_e32 v61, 2, v40
	v_xor_b32_e32 v40, 32, v38
	s_add_u32 s6, s96, s6
	v_readlane_b32 s40, v249, 18
	v_readlane_b32 s41, v249, 19
	v_readlane_b32 s42, v249, 20
	v_readlane_b32 s43, v249, 21
	v_readlane_b32 s44, v249, 22
	v_readlane_b32 s45, v249, 23
	v_readlane_b32 s46, v249, 24
	v_readlane_b32 s47, v249, 25
	v_cmp_lt_i32_e32 vcc, v40, v39
	s_addc_u32 s7, s97, s7
	s_lshl_b64 s[8:9], s[10:11], 11
	v_writelane_b32 v249, s10, 6
	v_cndmask_b32_e32 v38, v38, v40, vcc
	s_add_i32 s3, s18, s10
	v_writelane_b32 v249, s11, 7
	s_mov_b32 s20, s18
	v_lshlrev_b32_e32 v1, 2, v1
	v_lshlrev_b32_e32 v62, 2, v38
	s_ashr_i32 s10, s3, 31
	v_mov_b32_e32 v63, 0x358637bd
	s_mov_b32 s11, 0xe00000
	v_writelane_b32 v249, s20, 8
	s_nop 1
	v_writelane_b32 v249, s21, 9
	s_waitcnt vmcnt(0)
	s_branch .LBB0_93
; __device__ __forceinline__ unsigned pk2(float lo, float hi) { f32x2_t v = {lo, hi}; bf16x2_t b = __builtin_convertvector(v, bf16x2_t); return __builtin_bit_cast(unsigned, b); }
; __device__ __forceinline__ void p0_prologue(const Args& A, LAS unsigned char* lds, int tid, int lane, int wave) {
;     ...
;         for (; m < MTOT; m += NGW) {
;             const int mn = m + NGW;
;             if (mn < MTOT) { const float* xrow = mn < MP ? A.x_prompt + (size_t)mn * DM : A.x_sample + (size_t)(mn - MP) * DM; const float* prow = mn < MP ? A.p_prompt + (size_t)mn * PLE : A.p_sample + (size_t)(mn - MP) * PLE;
; #pragma unroll
;                 for (int j = 0; j < 4; ++j) nv[j] = *((const f32x4*)xrow + lane + 64 * j);
;                 npv = *((const f32x4*)prow + lane); }
;             float s = 0.f;
; #pragma unroll
;             for (int j = 0; j < 4; ++j) s += (v[j].x * v[j].x + v[j].y * v[j].y) + (v[j].z * v[j].z + v[j].w * v[j].w);
;             const float rstd = __builtin_amdgcn_rsqf(wave_sum(s) * (1.f / DM) + NORM_EPS);
;             u32x2* o8 = (u32x2*)(XN + (size_t)m * DM) + lane;
; #pragma unroll
;             for (int j = 0; j < 4; ++j) { u32x2 o; o.x = pk2(v[j].x * rstd * gv[j].x, v[j].y * rstd * gv[j].y); o.y = pk2(v[j].z * rstd * gv[j].z, v[j].w * rstd * gv[j].w); o8[64 * j] = o; }
;             u32x2 po; po.x = pk2(pv.x, pv.y); po.y = pk2(pv.z, pv.w);
;             *((u32x2*)(PB + (size_t)m * PLE) + lane) = po;
; #pragma unroll
;             for (int j = 0; j < 4; ++j) v[j] = nv[j];
;             pv = npv;
;         }
.LBB0_92:
	v_pk_mul_f32 v[68:69], v[36:37], v[36:37]
	v_pk_mul_f32 v[70:71], v[34:35], v[34:35]
	v_pk_mul_f32 v[64:65], v[32:33], v[32:33]
	v_pk_mul_f32 v[66:67], v[30:31], v[30:31]
	v_pk_mov_b32 v[72:73], v[70:71], v[68:69] op_sel:[1,0]
	v_mov_b32_e32 v71, v69
	v_pk_add_f32 v[68:69], v[72:73], v[70:71]
	v_pk_mov_b32 v[70:71], v[66:67], v[64:65] op_sel:[1,0]
	v_mov_b32_e32 v67, v65
	v_pk_add_f32 v[64:65], v[70:71], v[66:67]
	v_pk_add_f32 v[68:69], v[68:69], v[68:69] op_sel_hi:[0,1]
	v_pk_add_f32 v[64:65], v[64:65], v[64:65] op_sel_hi:[0,1]
	v_mul_f32_e32 v64, v26, v26
	v_pk_fma_f32 v[66:67], v[26:27], v[26:27], v[64:65] op_sel_hi:[1,1,0]
	v_mul_f32_e32 v64, v28, v28
	v_pk_fma_f32 v[70:71], v[28:29], v[28:29], v[64:65] op_sel_hi:[1,1,0]
	v_mul_f32_e32 v66, v22, v22
	v_mul_f32_e32 v70, v23, v23
	v_mul_f32_e32 v68, v24, v24
	v_mul_f32_e32 v64, v25, v25
	v_pk_add_f32 v[66:67], v[66:67], v[70:71]
	v_pk_add_f32 v[64:65], v[68:69], v[64:65]
	v_readlane_b32 s20, v249, 6
	v_pk_add_f32 v[64:65], v[66:67], v[64:65]
	s_add_i32 s18, s18, s20
	v_add_f32_e32 v64, v64, v65
	ds_bpermute_b32 v65, v1, v64
	v_cvt_pk_bf16_f32 v18, v18, v19
	v_cvt_pk_bf16_f32 v19, v20, v21
	v_lshl_add_u64 v[20:21], s[0:1], 0, v[130:131]
	s_add_u32 s0, s0, s4
	s_waitcnt lgkmcnt(0)
	v_add_f32_e32 v64, v64, v65
	ds_bpermute_b32 v65, v58, v64
	s_addc_u32 s1, s1, s5
	v_readlane_b32 s21, v249, 7
	s_waitcnt lgkmcnt(0)
	v_add_f32_e32 v64, v64, v65
	ds_bpermute_b32 v65, v59, v64
	s_waitcnt lgkmcnt(0)
	v_add_f32_e32 v64, v64, v65
	ds_bpermute_b32 v65, v60, v64
	s_waitcnt lgkmcnt(0)
	v_add_f32_e32 v64, v64, v65
	ds_bpermute_b32 v65, v61, v64
	s_waitcnt lgkmcnt(0)
	v_add_f32_e32 v66, v64, v65
	ds_bpermute_b32 v67, v62, v66
	v_lshl_add_u64 v[64:65], s[6:7], 0, v[130:131]
	s_add_u32 s6, s6, s8
	v_add_co_u32_e32 v64, vcc, s11, v64
	s_waitcnt lgkmcnt(0)
	v_add_f32_e32 v66, v66, v67
	v_fmamk_f32 v66, v66, 0x3a800000, v63
	v_rsq_f32_e32 v66, v66
	s_addc_u32 s7, s7, s9
	v_addc_co_u32_e32 v65, vcc, 0, v65, vcc
	v_pk_mul_f32 v[34:35], v[34:35], v[66:67] op_sel_hi:[1,0]
	v_pk_mul_f32 v[36:37], v[36:37], v[66:67] op_sel_hi:[1,0]
	v_pk_mul_f32 v[30:31], v[30:31], v[66:67] op_sel_hi:[1,0]
	v_pk_mul_f32 v[32:33], v[32:33], v[66:67] op_sel_hi:[1,0]
	v_pk_mul_f32 v[26:27], v[26:27], v[66:67] op_sel_hi:[1,0]
	v_pk_mul_f32 v[28:29], v[28:29], v[66:67] op_sel_hi:[1,0]
	v_pk_mul_f32 v[22:23], v[22:23], v[66:67] op_sel_hi:[1,0]
	v_pk_mul_f32 v[24:25], v[24:25], v[66:67] op_sel_hi:[1,0]
	v_pk_mul_f32 v[34:35], v[14:15], v[34:35]
	v_pk_mul_f32 v[36:37], v[16:17], v[36:37]
	v_pk_mul_f32 v[30:31], v[10:11], v[30:31]
	v_pk_mul_f32 v[32:33], v[12:13], v[32:33]
	v_pk_mul_f32 v[26:27], v[6:7], v[26:27]
	v_pk_mul_f32 v[28:29], v[8:9], v[28:29]
	v_pk_mul_f32 v[22:23], v[2:3], v[22:23]
	v_pk_mul_f32 v[24:25], v[4:5], v[24:25]
	v_cvt_pk_bf16_f32 v34, v34, v35
	v_cvt_pk_bf16_f32 v35, v36, v37
	v_cvt_pk_bf16_f32 v30, v30, v31
	v_cvt_pk_bf16_f32 v31, v32, v33
	v_cvt_pk_bf16_f32 v26, v26, v27
	v_cvt_pk_bf16_f32 v27, v28, v29
	v_cvt_pk_bf16_f32 v22, v22, v23
	v_cvt_pk_bf16_f32 v23, v24, v25
	s_add_u32 s3, s3, s20
	global_store_dwordx2 v[64:65], v[34:35], off
	global_store_dwordx2 v[64:65], v[30:31], off offset:512
	global_store_dwordx2 v[64:65], v[26:27], off offset:1024
	global_store_dwordx2 v[64:65], v[22:23], off offset:1536
	global_store_dwordx2 v[20:21], v[18:19], off
	s_addc_u32 s10, s10, s21
	s_waitcnt vmcnt(5)
	v_mov_b64_e32 v[18:19], v[54:55]
	s_cmp_lt_i32 s18, 0x8400
	v_mov_b64_e32 v[20:21], v[56:57]
	v_mov_b32_e32 v34, v50
	v_mov_b32_e32 v35, v51
	v_mov_b32_e32 v36, v52
	v_mov_b32_e32 v37, v53
	v_mov_b32_e32 v30, v46
	v_mov_b32_e32 v31, v47
	v_mov_b32_e32 v32, v48
	v_mov_b32_e32 v33, v49
	v_mov_b32_e32 v26, v42
	v_mov_b32_e32 v27, v43
	v_mov_b32_e32 v28, v44
	v_mov_b32_e32 v29, v45
	v_mov_b32_e32 v22, v38
	v_mov_b32_e32 v23, v39
	v_mov_b32_e32 v24, v40
	v_mov_b32_e32 v25, v41
	s_cbranch_scc0 .LBB0_95

; __global__ void __launch_bounds__(512, 2) hymba_fwd(Args A) {
;     ...
;     {
;         const int gw = blockIdx.x * 8 + wave, NGW = gridDim.x * 8;
;         f32x4 gv[4];
; #pragma unroll
;         for (int j = 0; j < 4; ++j) gv[j] = *((const f32x4*)A.g_final + lane + 64 * j);
;         u32x2 hw[4], nh[4]; float rs = 0.f, nrs = 0.f;
;         int m = gw;
;         if (m < MTOT) { const u32x2* hr = (const u32x2*)(XN + (size_t)m * DM) + lane;
; #pragma unroll
;             for (int j = 0; j < 4; ++j) hw[j] = hr[64 * j];
;             rs = rowss3[m]; }
;         for (; m < MTOT; m += NGW) {
;             const int mn = m + NGW;
;             if (mn < MTOT) { const u32x2* hr = (const u32x2*)(XN + (size_t)mn * DM) + lane;
; #pragma unroll
;                 for (int j = 0; j < 4; ++j) nh[j] = hr[64 * j];
;                 nrs = rowss3[mn]; }
;             const float rstd = __builtin_amdgcn_rsqf(rs * (1.f / DM) + NORM_EPS);
;             f32x4* yr = (f32x4*)(A.out + (size_t)m * DM) + lane;
; #pragma unroll
;             for (int j = 0; j < 4; ++j) { f32x4 v = {bflo(hw[j].x), bfhi(hw[j].x), bflo(hw[j].y), bfhi(hw[j].y)}; v = v * rstd * gv[j]; __builtin_nontemporal_store(v, &yr[64 * j]); }
; #pragma unroll
;             for (int j = 0; j < 4; ++j) hw[j] = nh[j];
;             rs = nrs;
;         }
.LBB0_646:
	s_or_b64 exec, exec, s[2:3]
	v_readlane_b32 s0, v249, 30
	v_readlane_b32 s1, v249, 31
	s_and_b64 vcc, exec, s[0:1]
	s_barrier
	s_cbranch_vccz .LBB0_651
	v_readlane_b32 s14, v249, 8
	v_readlane_b32 s15, v249, 9
	s_ashr_i32 s15, s14, 31
	s_lshl_b64 s[0:1], s[14:15], 11
	s_add_u32 s0, s68, s0
	s_addc_u32 s1, s69, s1
	s_lshl_b64 s[2:3], s[14:15], 2
	s_add_u32 s2, s12, s2
	v_mov_b32_e32 v129, 0
	global_load_dwordx4 v[0:3], v128, s[84:85]
	global_load_dwordx4 v[4:7], v128, s[84:85] offset:1024
	global_load_dwordx4 v[8:11], v128, s[84:85] offset:2048
	global_load_dwordx4 v[12:15], v128, s[84:85] offset:3072
	global_load_dwordx2 v[18:19], v130, s[0:1] offset:1536
	s_addc_u32 s3, s13, s3
	global_load_dwordx2 v[34:35], v130, s[0:1]
	global_load_dwordx2 v[28:29], v130, s[0:1] offset:512
	global_load_dwordx2 v[22:23], v130, s[0:1] offset:1024
	global_load_dword v38, v129, s[2:3]
	s_lshl_b64 s[0:1], s[14:15], 12
	s_add_u32 s0, s86, s0
	v_readlane_b32 s12, v249, 6
	s_addc_u32 s1, s87, s1
	v_readlane_b32 s13, v249, 7
	s_add_i32 s4, s14, s12
	s_ashr_i32 s13, s12, 31
	s_ashr_i32 s5, s4, 31
	v_lshl_add_u64 v[16:17], s[0:1], 0, v[128:129]
	s_lshl_b64 s[0:1], s[12:13], 12
	s_lshl_b64 s[2:3], s[4:5], 2
	s_add_u32 s8, s2, 0x22000
	s_addc_u32 s9, s3, 0
	s_lshl_b64 s[4:5], s[4:5], 11
	s_lshl_b64 s[2:3], s[12:13], 2
	v_or_b32_e32 v20, s4, v130
	v_mov_b32_e32 v21, s5
	s_lshl_b64 s[4:5], s[12:13], 11
	v_mov_b32_e32 v36, 0x358637bd
	v_mov_b32_e32 v37, 0
	v_mov_b32_e32 v24, 0
	v_mov_b32_e32 v25, v129
	v_mov_b32_e32 v26, 0
	v_mov_b32_e32 v27, v129
	v_mov_b32_e32 v30, 0
	v_mov_b32_e32 v31, v129
	v_mov_b32_e32 v32, 0
	v_mov_b32_e32 v33, v129
	s_waitcnt vmcnt(0)
	s_branch .LBB0_649
.LBB0_648:
	v_fmamk_f32 v38, v38, 0x3a800000, v36
	v_rsq_f32_e32 v42, v38
	v_lshlrev_b32_e32 v38, 16, v34
	v_and_b32_e32 v39, 0xffff0000, v34
	v_lshlrev_b32_e32 v34, 16, v35
	v_and_b32_e32 v35, 0xffff0000, v35
	v_pk_mul_f32 v[34:35], v[42:43], v[34:35] op_sel_hi:[0,1]
	v_pk_mul_f32 v[38:39], v[42:43], v[38:39] op_sel_hi:[0,1]
	v_pk_mul_f32 v[40:41], v[2:3], v[34:35]
	v_lshlrev_b32_e32 v34, 16, v28
	v_and_b32_e32 v35, 0xffff0000, v28
	v_lshlrev_b32_e32 v28, 16, v29
	v_and_b32_e32 v29, 0xffff0000, v29
	v_pk_mul_f32 v[38:39], v[0:1], v[38:39]
	v_pk_mul_f32 v[28:29], v[42:43], v[28:29] op_sel_hi:[0,1]
	global_store_dwordx4 v[16:17], v[38:41], off nt
	v_pk_mul_f32 v[34:35], v[42:43], v[34:35] op_sel_hi:[0,1]
	s_add_u32 s8, s8, s2
	v_pk_mul_f32 v[40:41], v[6:7], v[28:29]
	v_lshlrev_b32_e32 v28, 16, v22
	v_and_b32_e32 v29, 0xffff0000, v22
	v_lshlrev_b32_e32 v22, 16, v23
	v_and_b32_e32 v23, 0xffff0000, v23
	v_pk_mul_f32 v[38:39], v[4:5], v[34:35]
	v_pk_mul_f32 v[22:23], v[42:43], v[22:23] op_sel_hi:[0,1]
	global_store_dwordx4 v[16:17], v[38:41], off offset:1024 nt
	v_pk_mul_f32 v[28:29], v[42:43], v[28:29] op_sel_hi:[0,1]
	s_addc_u32 s9, s9, s3
	v_pk_mul_f32 v[40:41], v[10:11], v[22:23]
	v_lshlrev_b32_e32 v22, 16, v18
	v_and_b32_e32 v23, 0xffff0000, v18
	v_lshlrev_b32_e32 v18, 16, v19
	v_and_b32_e32 v19, 0xffff0000, v19
	v_pk_mul_f32 v[38:39], v[8:9], v[28:29]
	v_pk_mul_f32 v[22:23], v[42:43], v[22:23] op_sel_hi:[0,1]
	v_pk_mul_f32 v[18:19], v[42:43], v[18:19] op_sel_hi:[0,1]
	global_store_dwordx4 v[16:17], v[38:41], off offset:2048 nt
	v_lshl_add_u64 v[20:21], v[20:21], 0, s[4:5]
	s_andn2_b64 vcc, exec, s[6:7]
	v_pk_mul_f32 v[40:41], v[14:15], v[18:19]
	v_pk_mul_f32 v[38:39], v[12:13], v[22:23]
	global_store_dwordx4 v[16:17], v[38:41], off offset:3072 nt
	v_lshl_add_u64 v[16:17], v[16:17], 0, s[0:1]
	s_waitcnt vmcnt(4)
	v_mov_b32_e32 v34, v24
	v_mov_b32_e32 v38, v37
	v_mov_b32_e32 v35, v25
	v_mov_b32_e32 v28, v26
	v_mov_b32_e32 v29, v27
	v_mov_b32_e32 v22, v30
	v_mov_b32_e32 v23, v31
	v_mov_b32_e32 v18, v32
	v_mov_b32_e32 v19, v33
	s_cbranch_vccz .LBB0_651
